# final rmsnorm loop: gain vector loaded once, per-chunk vmcnt(0) drains removed, next item's rows prefetched before the current stores
# speedup vs baseline: 1.0085x; 1.0024x over previous
; DI int ltid_w(int wave) { int t; asm volatile("v_mbcnt_lo_u32_b32 %0, -1, 0\n\tv_mbcnt_hi_u32_b32 %0, -1, %0" : "=v"(t)); return (wave << 6) | t; }
; DI void ph_final(const Params& p, int bid, int nb) {
;   const int tid_ = ltid_w(p.wave); const int lane = tid_ & 63, w = tid_ >> 6;
;   for (int it = bid; it < NB * NLAT / 8; it += nb) {
;     float4 v[2][4];
; #pragma unroll
;     for (int rr = 0; rr < 2; ++rr) {
;       const float* rp = p.out + (size_t)(it * 8 + rr * 4 + w) * DM;
; #pragma unroll
;       for (int i = 0; i < 4; ++i) v[rr][i] = *(const float4*)(rp + (i * 64 + lane) * 4);
;     ...
;         const float4 gg = *(const float4*)(p.final_g + j);
.LBB0_1130:
	s_cmp_lt_i32 s58, 14
	s_cselect_b64 s[0:1], -1, 0
	s_cmp_gt_i32 s59, 13
	s_cselect_b64 s[2:3], -1, 0
	s_and_b64 s[0:1], s[0:1], s[2:3]
	s_and_b64 vcc, exec, s[0:1]
	s_cbranch_vccz .LBB0_1134
	s_cmpk_gt_i32 s70, 0x7ff
	v_mbcnt_lo_u32_b32 v0, -1, 0
	v_mbcnt_hi_u32_b32 v0, -1, v0
	s_cbranch_scc1 .LBB0_1134
	v_readlane_b32 s0, v253, 0
	v_cmp_lt_i32_e32 vcc, v184, v178
	v_mov_b32_e32 v3, 0
	v_or_b32_e32 v1, s0, v0
	v_ashrrev_i32_e32 v4, 6, v1
	v_cndmask_b32_e32 v1, v177, v184, vcc
	v_cmp_lt_i32_e32 vcc, v183, v178
	v_lshlrev_b32_e32 v7, 2, v1
	v_lshlrev_b32_e32 v0, 4, v0
	v_cndmask_b32_e32 v1, v177, v183, vcc
	v_cmp_lt_i32_e32 vcc, v182, v178
	v_lshlrev_b32_e32 v10, 2, v1
	v_readlane_b32 s0, v253, 3
	v_cndmask_b32_e32 v1, v177, v182, vcc
	v_cmp_lt_i32_e32 vcc, v181, v178
	v_lshlrev_b32_e32 v11, 2, v1
	v_and_b32_e32 v2, 0x3f0, v0
	v_cndmask_b32_e32 v1, v177, v181, vcc
	v_cmp_lt_i32_e32 vcc, v180, v178
	v_lshlrev_b32_e32 v12, 2, v1
	v_readlane_b32 s1, v253, 4
	v_cndmask_b32_e32 v1, v177, v180, vcc
	v_cmp_lt_i32_e32 vcc, v179, v178
	v_lshlrev_b32_e32 v13, 2, v1
	v_readlane_b32 s2, v253, 5
	v_cndmask_b32_e32 v1, v177, v179, vcc
	v_lshlrev_b32_e32 v14, 2, v1
	v_readlane_b32 s3, v253, 6
	v_lshl_add_u64 v[0:1], s[0:1], 0, v[2:3]
	v_readlane_b32 s0, v254, 10
	v_lshl_add_u64 v[2:3], s[2:3], 0, v[2:3]
	v_mov_b32_e32 v6, 0x358637bd
	v_add_u32_e32 v4, s0, v4
	s_mov_b32 s0, 0x3a800000
	s_mov_b32 s1, 0x800000
	v_readlane_b32 s2, v254, 11
	global_load_dwordx4 v[86:89], v[0:1], off
	global_load_dwordx4 v[90:93], v[0:1], off offset:1024
	global_load_dwordx4 v[94:97], v[0:1], off offset:2048
	global_load_dwordx4 v[98:101], v[0:1], off offset:3072
	v_ashrrev_i32_e32 v5, 31, v4
	v_lshlrev_b64 v[134:135], 12, v[4:5]
	v_lshl_add_u64 v[134:135], v[2:3], 0, v[134:135]
	v_add_u32_e32 v136, 4, v4
	v_ashrrev_i32_e32 v137, 31, v136
	v_lshlrev_b64 v[136:137], 12, v[136:137]
	v_lshl_add_u64 v[136:137], v[2:3], 0, v[136:137]
	global_load_dwordx4 v[102:105], v[134:135], off
	global_load_dwordx4 v[106:109], v[134:135], off offset:1024
	global_load_dwordx4 v[110:113], v[134:135], off offset:2048
	global_load_dwordx4 v[114:117], v[134:135], off offset:3072
	global_load_dwordx4 v[118:121], v[136:137], off
	global_load_dwordx4 v[122:125], v[136:137], off offset:1024
	global_load_dwordx4 v[126:129], v[136:137], off offset:2048
	global_load_dwordx4 v[130:133], v[136:137], off offset:3072
	s_waitcnt vmcnt(0)
.LBB0_1133:
	s_waitcnt vmcnt(8)
	v_mov_b32_e32 v16, v102
	v_mov_b32_e32 v17, v103
	v_mov_b32_e32 v18, v104
	v_mov_b32_e32 v19, v105
	v_mov_b32_e32 v20, v106
	v_mov_b32_e32 v21, v107
	v_mov_b32_e32 v22, v108
	v_mov_b32_e32 v23, v109
	v_mov_b32_e32 v24, v110
	v_mov_b32_e32 v25, v111
	v_mov_b32_e32 v26, v112
	v_mov_b32_e32 v27, v113
	v_mov_b32_e32 v28, v114
	v_mov_b32_e32 v29, v115
	v_mov_b32_e32 v30, v116
	v_mov_b32_e32 v31, v117
	v_mov_b32_e32 v32, v118
	v_mov_b32_e32 v33, v119
	v_mov_b32_e32 v34, v120
	v_mov_b32_e32 v35, v121
	v_mov_b32_e32 v36, v122
	v_mov_b32_e32 v37, v123
	v_mov_b32_e32 v38, v124
	v_mov_b32_e32 v39, v125
	v_mov_b32_e32 v40, v126
	v_mov_b32_e32 v41, v127
	v_mov_b32_e32 v42, v128
	v_mov_b32_e32 v43, v129
	v_mov_b32_e32 v44, v130
	v_mov_b32_e32 v45, v131
	v_mov_b32_e32 v46, v132
	v_mov_b32_e32 v47, v133
	v_mov_b32_e32 v52, v134
	v_mov_b32_e32 v53, v135
	v_mov_b32_e32 v8, v136
	v_mov_b32_e32 v9, v137
	s_add_i32 s70, s70, s54
	s_cmpk_lt_i32 s70, 0x800
	v_add_u32_e32 v4, s2, v4
	s_cbranch_scc0 .Lfn_nopf
	v_ashrrev_i32_e32 v5, 31, v4
	v_lshlrev_b64 v[134:135], 12, v[4:5]
	v_lshl_add_u64 v[134:135], v[2:3], 0, v[134:135]
	v_add_u32_e32 v136, 4, v4
	v_ashrrev_i32_e32 v137, 31, v136
	v_lshlrev_b64 v[136:137], 12, v[136:137]
	v_lshl_add_u64 v[136:137], v[2:3], 0, v[136:137]
	global_load_dwordx4 v[102:105], v[134:135], off
	global_load_dwordx4 v[106:109], v[134:135], off offset:1024
	global_load_dwordx4 v[110:113], v[134:135], off offset:2048
	global_load_dwordx4 v[114:117], v[134:135], off offset:3072
	global_load_dwordx4 v[118:121], v[136:137], off
	global_load_dwordx4 v[122:125], v[136:137], off offset:1024
	global_load_dwordx4 v[126:129], v[136:137], off offset:2048
	global_load_dwordx4 v[130:133], v[136:137], off offset:3072
; DI void ph_final(const Params& p, int bid, int nb) {
;     ...
; #pragma unroll
;     for (int rr = 0; rr < 2; ++rr) {
;       float* rp = p.out + (size_t)(it * 8 + rr * 4 + w) * DM;
;       float ss = 0.f;
; #pragma unroll
;       for (int i = 0; i < 4; ++i) ss += v[rr][i].x * v[rr][i].x + v[rr][i].y * v[rr][i].y + v[rr][i].z * v[rr][i].z + v[rr][i].w * v[rr][i].w;
;       ss = wave_sum(ss);
;       const float rstd = rsqrtf(ss * (1.f / DM) + EPS);
; #pragma unroll
;       for (int i = 0; i < 4; ++i) {
;         const int j = (i * 64 + lane) * 4;
;         const float4 gg = *(const float4*)(p.final_g + j);
;         float4 o;
;         o.x = v[rr][i].x * rstd * gg.x; o.y = v[rr][i].y * rstd * gg.y; o.z = v[rr][i].z * rstd * gg.z; o.w = v[rr][i].w * rstd * gg.w;
;         {
;           typedef float f32x4_t __attribute__((ext_vector_type(4)));
;           const f32x4_t ov = {o.x, o.y, o.z, o.w};
;           __builtin_nontemporal_store(ov, (f32x4_t*)(rp + j));
;         }
;       }
.Lfn_nopf:
	v_mov_b32_e32 v56, v17
	v_mov_b32_e32 v57, v21
	v_mov_b32_e32 v64, v25
	v_mov_b32_e32 v65, v29
	v_mov_b32_e32 v54, v16
	v_mov_b32_e32 v55, v20
	v_mov_b32_e32 v62, v24
	v_mov_b32_e32 v63, v28
	v_pk_mul_f32 v[56:57], v[56:57], v[56:57]
	v_pk_mul_f32 v[64:65], v[64:65], v[64:65]
	v_mov_b32_e32 v72, v33
	v_mov_b32_e32 v73, v37
	v_mov_b32_e32 v58, v18
	v_mov_b32_e32 v59, v22
	v_mov_b32_e32 v70, v32
	v_mov_b32_e32 v71, v36
	v_mov_b32_e32 v80, v41
	v_mov_b32_e32 v81, v45
	v_pk_fma_f32 v[54:55], v[54:55], v[54:55], v[56:57]
	v_pk_fma_f32 v[56:57], v[62:63], v[62:63], v[64:65]
	v_pk_mul_f32 v[62:63], v[72:73], v[72:73]
	v_mov_b32_e32 v74, v34
	v_mov_b32_e32 v75, v38
	v_mov_b32_e32 v78, v40
	v_mov_b32_e32 v79, v44
	v_pk_mul_f32 v[64:65], v[80:81], v[80:81]
	v_pk_fma_f32 v[54:55], v[58:59], v[58:59], v[54:55]
	v_pk_fma_f32 v[58:59], v[70:71], v[70:71], v[62:63]
	v_mov_b32_e32 v60, v19
	v_mov_b32_e32 v61, v23
	v_mov_b32_e32 v66, v26
	v_mov_b32_e32 v67, v30
	v_mov_b32_e32 v76, v35
	v_mov_b32_e32 v77, v39
	v_mov_b32_e32 v82, v42
	v_mov_b32_e32 v83, v46
	v_pk_fma_f32 v[62:63], v[78:79], v[78:79], v[64:65]
	v_pk_fma_f32 v[58:59], v[74:75], v[74:75], v[58:59]
	v_mov_b32_e32 v68, v27
	v_mov_b32_e32 v69, v31
	v_mov_b32_e32 v84, v43
	v_mov_b32_e32 v85, v47
	v_pk_fma_f32 v[56:57], v[66:67], v[66:67], v[56:57]
	v_pk_fma_f32 v[54:55], v[60:61], v[60:61], v[54:55]
	v_pk_fma_f32 v[60:61], v[82:83], v[82:83], v[62:63]
	v_pk_fma_f32 v[58:59], v[76:77], v[76:77], v[58:59]
	v_pk_fma_f32 v[56:57], v[68:69], v[68:69], v[56:57]
	v_pk_fma_f32 v[60:61], v[84:85], v[84:85], v[60:61]
	v_mov_b32_e32 v63, v54
	v_mov_b32_e32 v62, v58
	v_mov_b32_e32 v54, v59
	v_mov_b32_e32 v65, v56
	v_mov_b32_e32 v64, v60
	v_pk_add_f32 v[54:55], v[62:63], v[54:55]
	v_mov_b32_e32 v56, v61
	v_pk_add_f32 v[54:55], v[54:55], v[64:65]
	s_nop 0
	v_pk_add_f32 v[54:55], v[54:55], v[56:57]
	ds_bpermute_b32 v57, v7, v55
	ds_bpermute_b32 v56, v7, v54
	s_waitcnt lgkmcnt(0)
	v_pk_add_f32 v[54:55], v[54:55], v[56:57]
	ds_bpermute_b32 v57, v10, v55
	ds_bpermute_b32 v56, v10, v54
	s_waitcnt lgkmcnt(0)
	v_pk_add_f32 v[54:55], v[54:55], v[56:57]
	ds_bpermute_b32 v57, v11, v55
	ds_bpermute_b32 v56, v11, v54
	s_waitcnt lgkmcnt(0)
	v_pk_add_f32 v[54:55], v[54:55], v[56:57]
	ds_bpermute_b32 v57, v12, v55
	ds_bpermute_b32 v56, v12, v54
	s_waitcnt lgkmcnt(0)
	v_pk_add_f32 v[54:55], v[54:55], v[56:57]
	ds_bpermute_b32 v57, v13, v55
	ds_bpermute_b32 v56, v13, v54
	s_waitcnt lgkmcnt(0)
	v_pk_add_f32 v[54:55], v[54:55], v[56:57]
	ds_bpermute_b32 v57, v14, v55
	ds_bpermute_b32 v56, v14, v54
	s_waitcnt lgkmcnt(0)
	v_pk_add_f32 v[54:55], v[54:55], v[56:57]
	s_nop 0
	v_pk_fma_f32 v[54:55], v[54:55], s[0:1], v[6:7] op_sel_hi:[1,0,0]
	s_nop 0
	v_mul_f32_e32 v5, 0x4b800000, v55
	v_cmp_gt_f32_e32 vcc, s1, v55
	s_nop 1
	v_cndmask_b32_e32 v5, v55, v5, vcc
	v_rsq_f32_e32 v5, v5
	s_nop 0
	v_mul_f32_e32 v15, 0x45800000, v5
	v_cndmask_b32_e32 v56, v5, v15, vcc
	v_pk_mul_f32 v[16:17], v[16:17], v[56:57] op_sel_hi:[1,0]
	v_pk_mul_f32 v[18:19], v[18:19], v[56:57] op_sel_hi:[1,0]
	v_pk_mul_f32 v[16:17], v[86:87], v[16:17]
	v_pk_mul_f32 v[18:19], v[88:89], v[18:19]
	global_store_dwordx4 v[52:53], v[16:19], off nt
	v_pk_mul_f32 v[22:23], v[22:23], v[56:57] op_sel_hi:[1,0]
	v_pk_mul_f32 v[20:21], v[20:21], v[56:57] op_sel_hi:[1,0]
	v_mul_f32_e32 v5, 0x4b800000, v54
	v_cmp_gt_f32_e32 vcc, s1, v54
	v_pk_mul_f32 v[16:17], v[90:91], v[20:21]
	v_pk_mul_f32 v[18:19], v[92:93], v[22:23]
	global_store_dwordx4 v[52:53], v[16:19], off offset:1024 nt
	v_pk_mul_f32 v[20:21], v[26:27], v[56:57] op_sel_hi:[1,0]
	v_pk_mul_f32 v[22:23], v[24:25], v[56:57] op_sel_hi:[1,0]
	v_cndmask_b32_e32 v5, v54, v5, vcc
	v_rsq_f32_e32 v5, v5
	v_pk_mul_f32 v[16:17], v[22:23], v[94:95]
	v_pk_mul_f32 v[18:19], v[20:21], v[96:97]
	global_store_dwordx4 v[52:53], v[16:19], off offset:2048 nt
	v_pk_mul_f32 v[20:21], v[30:31], v[56:57] op_sel_hi:[1,0]
	v_pk_mul_f32 v[22:23], v[28:29], v[56:57] op_sel_hi:[1,0]
	v_mul_f32_e32 v15, 0x45800000, v5
	v_pk_mul_f32 v[16:17], v[22:23], v[98:99]
	v_pk_mul_f32 v[18:19], v[20:21], v[100:101]
	global_store_dwordx4 v[52:53], v[16:19], off offset:3072 nt
	v_cndmask_b32_e32 v20, v5, v15, vcc
	v_pk_mul_f32 v[22:23], v[34:35], v[20:21] op_sel_hi:[1,0]
	v_pk_mul_f32 v[24:25], v[32:33], v[20:21] op_sel_hi:[1,0]
	v_pk_mul_f32 v[18:19], v[88:89], v[22:23]
	v_pk_mul_f32 v[16:17], v[86:87], v[24:25]
	global_store_dwordx4 v[8:9], v[16:19], off nt
	v_pk_mul_f32 v[22:23], v[38:39], v[20:21] op_sel_hi:[1,0]
	v_pk_mul_f32 v[24:25], v[36:37], v[20:21] op_sel_hi:[1,0]
	v_pk_mul_f32 v[18:19], v[92:93], v[22:23]
	v_pk_mul_f32 v[16:17], v[90:91], v[24:25]
	global_store_dwordx4 v[8:9], v[16:19], off offset:1024 nt
	v_pk_mul_f32 v[22:23], v[42:43], v[20:21] op_sel_hi:[1,0]
	v_pk_mul_f32 v[24:25], v[40:41], v[20:21] op_sel_hi:[1,0]
	v_pk_mul_f32 v[18:19], v[22:23], v[96:97]
	v_pk_mul_f32 v[16:17], v[24:25], v[94:95]
	global_store_dwordx4 v[8:9], v[16:19], off offset:2048 nt
	v_pk_mul_f32 v[22:23], v[46:47], v[20:21] op_sel_hi:[1,0]
	v_pk_mul_f32 v[20:21], v[44:45], v[20:21] op_sel_hi:[1,0]
	v_pk_mul_f32 v[18:19], v[22:23], v[100:101]
	v_pk_mul_f32 v[16:17], v[20:21], v[98:99]
	global_store_dwordx4 v[8:9], v[16:19], off offset:3072 nt
	s_cbranch_scc1 .LBB0_1133
